# weight transposes for later phases deferred to idle WGs in P1 last round
# speedup vs baseline: 1.0171x; 1.0171x over previous
; #define LAS __attribute__((address_space(3)))
;     if (ldd == 0) ldd = K;
;     const int tid = threadIdx.x; const int ntk = K / 64, ntn = Ndst / 64;
;     for (int t = blockIdx.x; t < ntk * ntn; t += gridDim.x) {
;         const int tn = t / ntk, tk = t - tn * ntk; const int n0 = tn * 64, k0 = tk * 64;
;         int s0 = n0, nvalid = 64;
;         if (kind == 1) { if (n0 < 3072) s0 = n0; else if (n0 < 7680) s0 = n0 + 16; else if (n0 == 7680) { s0 = 3072; nvalid = 16; } else { s0 = 0; nvalid = 0; } }
;         else if (kind == 2) { const int pn = n0 >> 8, j0 = n0 & 255; s0 = (j0 < 128) ? pn * 128 + j0 : DFF + pn * 128 + (j0 - 128); }
; #pragma unroll
;         for (int i = 0; i < 2; ++i) { const int idx = tid + 512 * i, kk = idx >> 4, n4 = idx & 15;
;             f32x4 v = {0.f, 0.f, 0.f, 0.f};
;             if (n4 * 4 < nvalid) v = *(const f32x4*)(src + (size_t)(k0 + kk) * Nsrc + s0 + n4 * 4);
;             const float gg = gain ? gain[k0 + kk] : 1.0f;
; #pragma unroll
;             for (int j = 0; j < 4; ++j) tile[kk * 65 + n4 * 4 + j] = v[j] * gg; }
; __global__ void __launch_bounds__(512, 2) fwd_megakernel(Params p) {
;     ...
;     bf16_t* WIN = (bf16_t*)(ws + WS_WIN); bf16_t* WA = (bf16_t*)(ws + WS_WA); bf16_t* WB = (bf16_t*)(ws + WS_WB); bf16_t* WOUT = (bf16_t*)(ws + WS_WOUT);
;     bf16_t* WFIN = (bf16_t*)(ws + WS_WFIN); bf16_t* WFOUT = (bf16_t*)(ws + WS_WFOUT); bf16_t* WGLU = (bf16_t*)(ws + WS_WGLU);
;     bf16_t* XB = (bf16_t*)(ws + WS_XB); bf16_t* MIX = (bf16_t*)(ws + WS_Q); bf16_t* HID = (bf16_t*)(ws + WS_PROJ);
;     float* RSTD1 = (float*)(ws + WS_RSTD1); unsigned long long* SSQ2 = (unsigned long long*)(ws + WS_SSQ2); unsigned long long* SSQ3 = (unsigned long long*)(ws + WS_SSQ3);
;     if (IN(0)) {
;         LAS float* tile = (LAS float*)lds;
;         transpose_job(tile, p.w_in, WIN, p.norm1_g, 2048, 7696, NIN, 1);
.LBB0_17:
	s_load_dwordx16 s[4:19], s[0:1], 0x40
	s_waitcnt lgkmcnt(0)
	v_writelane_b32 v246, s4, 6
	s_nop 1
	v_writelane_b32 v246, s5, 7
	v_writelane_b32 v246, s6, 8
	v_writelane_b32 v246, s7, 9
	v_writelane_b32 v246, s8, 10
	v_writelane_b32 v246, s9, 11
	v_writelane_b32 v246, s10, 12
	v_writelane_b32 v246, s11, 13
	v_writelane_b32 v246, s12, 14
	v_writelane_b32 v246, s13, 15
	v_writelane_b32 v246, s14, 16
	v_writelane_b32 v246, s15, 17
	v_writelane_b32 v246, s16, 18
	v_writelane_b32 v246, s17, 19
	v_writelane_b32 v246, s18, 20
	v_writelane_b32 v246, s19, 21
	s_load_dwordx16 s[4:19], s[0:1], 0x80
	s_waitcnt lgkmcnt(0)
	v_writelane_b32 v246, s4, 22
	s_nop 1
	v_writelane_b32 v246, s5, 23
	v_writelane_b32 v246, s6, 24
	v_writelane_b32 v246, s7, 25
	v_writelane_b32 v246, s8, 26
	v_writelane_b32 v246, s9, 27
	v_writelane_b32 v246, s10, 28
	v_writelane_b32 v246, s11, 29
	v_writelane_b32 v246, s12, 30
	v_writelane_b32 v246, s13, 31
	v_writelane_b32 v246, s14, 32
	v_writelane_b32 v246, s15, 33
	v_writelane_b32 v246, s16, 34
	v_writelane_b32 v246, s17, 35
	v_writelane_b32 v246, s18, 36
	v_writelane_b32 v246, s19, 37
	s_add_u32 s8, s36, 0x23c0000
	s_addc_u32 s9, s37, 0
	s_add_u32 s0, s36, 0x42c0000
	s_addc_u32 s1, s37, 0
	v_writelane_b32 v246, s0, 38
	s_nop 1
	v_writelane_b32 v246, s1, 39
	s_add_u32 s0, s36, 0x48c0000
	s_addc_u32 s1, s37, 0
	v_writelane_b32 v246, s0, 40
	s_nop 1
	v_writelane_b32 v246, s1, 41
	s_add_u32 s0, s36, 0x50c0000
	s_addc_u32 s1, s37, 0
	v_writelane_b32 v246, s0, 42
	s_nop 1
	v_writelane_b32 v246, s1, 43
	s_add_u32 s0, s36, 0x7cc0000
	s_addc_u32 s1, s37, 0
	s_add_u32 s88, s36, 0x92c0000
	v_writelane_b32 v246, s0, 44
	s_addc_u32 s89, s37, 0
	s_nop 0
	v_writelane_b32 v246, s1, 45
	s_add_u32 s0, s36, 0x9340000
	s_addc_u32 s1, s37, 0
	v_writelane_b32 v246, s0, 46
	s_cmp_lt_i32 s38, 1
	s_nop 0
	v_writelane_b32 v246, s1, 47
	s_cselect_b64 s[0:1], -1, 0
	s_cmp_gt_i32 s39, 0
	s_cselect_b64 s[2:3], -1, 0
	s_and_b64 s[6:7], s[0:1], s[2:3]
	s_andn2_b64 vcc, exec, s[6:7]
	s_cbranch_vccnz .LBB0_67
	s_mov_b32 s17, s96
	s_mov_b32 s5, s62
	s_mov_b32 s13, 0xf80
	s_mov_b32 s27, 0
.Lp0_entry:
	v_and_b32_e32 v1, 63, v220
	v_lshrrev_b32_e32 v2, 6, v220
	v_lshrrev_b32_e32 v3, 4, v1
	v_and_b32_e32 v4, 15, v1
	v_readfirstlane_b32 s53, v2
	v_lshl_add_u32 v3, v2, 2, v3
	v_lshrrev_b32_e32 v8, 3, v220
	v_and_b32_e32 v9, 7, v220
	v_add_u32_e32 v7, 32, v3
	s_lshr_b32 s54, s53, 1
	s_lshl_b32 s54, s54, 1
	s_or_b32 s55, s54, 8
	s_lshl_b32 s53, s53, 10
	v_xor_b32_e32 v5, s54, v4
	v_xor_b32_e32 v6, s55, v4
	v_lshlrev_b32_e32 v5, 4, v5
	v_lshlrev_b32_e32 v6, 4, v6
	v_lshrrev_b32_e32 v10, 2, v8
	v_lshlrev_b32_e32 v11, 1, v9
	v_xor_b32_e32 v10, v10, v11
	v_lshlrev_b32_e32 v10, 4, v10
	v_and_b32_e32 v11, 3, v8
	v_lshl_add_u32 v10, v11, 2, v10
	v_lshl_add_u32 v10, v9, 11, v10
	v_lshlrev_b32_e32 v12, 5, v9
	v_lshlrev_b32_e32 v13, 4, v9
	s_mov_b32 s1, 0
	s_mov_b32 s3, s17

;     if (ldd == 0) ldd = K;
;     const int tid = threadIdx.x; const int ntk = K / 64, ntn = Ndst / 64;
;     for (int t = blockIdx.x; t < ntk * ntn; t += gridDim.x) {
;         const int tn = t / ntk, tk = t - tn * ntk; const int n0 = tn * 64, k0 = tk * 64;
;         int s0 = n0, nvalid = 64;
;         if (kind == 1) { if (n0 < 3072) s0 = n0; else if (n0 < 7680) s0 = n0 + 16; else if (n0 == 7680) { s0 = 3072; nvalid = 16; } else { s0 = 0; nvalid = 0; } }
;         else if (kind == 2) { const int pn = n0 >> 8, j0 = n0 & 255; s0 = (j0 < 128) ? pn * 128 + j0 : DFF + pn * 128 + (j0 - 128); }
; #pragma unroll
;         for (int i = 0; i < 2; ++i) { const int idx = tid + 512 * i, kk = idx >> 4, n4 = idx & 15;
;             f32x4 v = {0.f, 0.f, 0.f, 0.f};
;             if (n4 * 4 < nvalid) v = *(const f32x4*)(src + (size_t)(k0 + kk) * Nsrc + s0 + n4 * 4);
;             const float gg = gain ? gain[k0 + kk] : 1.0f;
; #pragma unroll
;             for (int j = 0; j < 4; ++j) tile[kk * 65 + n4 * 4 + j] = v[j] * gg; }
.Lp0_ret_pro:
	v_mad_u32_u24 v17, v3, s12, v5
	v_mad_u32_u24 v18, v7, s12, v6
	s_lshl_b32 s25, s1, 14
	s_add_u32 s25, s25, s53
	s_mov_b32 m0, s25
	s_add_u32 s25, s25, 0x2000
	global_load_lds_dwordx4 v17, s[10:11]
	s_mov_b32 m0, s25
	s_nop 0
	global_load_lds_dwordx4 v18, s[10:11]
	s_add_u32 s3, s3, s5
	s_add_u32 s1, s1, 1
	s_cmp_lt_u32 s1, 3
	s_cbranch_scc1 .Lp0_pro_loop
	s_mov_b32 s1, 0
	s_mov_b32 s0, s17
	s_mov_b32 s2, 0
.Lp0_loop:
	s_mul_i32 s3, s5, 3
	s_add_u32 s3, s3, s0
	s_cmp_lt_u32 s3, s13
	s_cselect_b32 s54, 1, 0
	s_cbranch_scc0 .Lp0_nodec
	s_mov_b32 s40, s3
	s_mov_b32 s52, 0
	s_branch .Lp0_dec

;     ...
;         for (int i = 0; i < 2; ++i) { const int idx = tid + 512 * i, kk = idx >> 4, n4 = idx & 15;
;             f32x4 v = {0.f, 0.f, 0.f, 0.f};
;             if (n4 * 4 < nvalid) v = *(const f32x4*)(src + (size_t)(k0 + kk) * Nsrc + s0 + n4 * 4);
;             const float gg = gain ? gain[k0 + kk] : 1.0f;
; #pragma unroll
;             for (int j = 0; j < 4; ++j) tile[kk * 65 + n4 * 4 + j] = v[j] * gg; }
;         __syncthreads();
;         { const int n = tid >> 3, k8 = tid & 7; float f[8];
; #pragma unroll
;             for (int j = 0; j < 8; ++j) f[j] = tile[(k8 * 8 + j) * 65 + n];
;             u32x4 w; w.x = pk_bf16(f[0], f[1]); w.y = pk_bf16(f[2], f[3]); w.z = pk_bf16(f[4], f[5]); w.w = pk_bf16(f[6], f[7]);
;             *(u32x4*)(dst + (size_t)(n0 + n) * ldd + koff + k0 + k8 * 8) = w; }
.Lp0_ret_cons:
	global_load_dwordx4 v[20:23], v12, s[18:19]
	global_load_dwordx4 v[24:27], v12, s[18:19] offset:16
	v_mad_u32_u24 v14, v8, s16, v13
	v_add_u32_e32 v15, s2, v10
	v_add_u32_e32 v16, 0x400, v15
	s_lshl_b32 s4, s5, 1
	s_add_u32 s4, s4, s0
	s_cmp_lt_u32 s4, s13
	s_cbranch_scc0 .Lp0_w_tail
	s_cmp_ge_u32 s1, 3
	s_cbranch_scc0 .Lp0_w_early
	s_waitcnt vmcnt(13)
	s_branch .Lp0_w_done

;     ...
;     const int tid = threadIdx.x; const int ntk = K / 64, ntn = Ndst / 64;
;     for (int t = blockIdx.x; t < ntk * ntn; t += gridDim.x) {
;         const int tn = t / ntk, tk = t - tn * ntk; const int n0 = tn * 64, k0 = tk * 64;
;         int s0 = n0, nvalid = 64;
;         if (kind == 1) { if (n0 < 3072) s0 = n0; else if (n0 < 7680) s0 = n0 + 16; else if (n0 == 7680) { s0 = 3072; nvalid = 16; } else { s0 = 0; nvalid = 0; } }
;         else if (kind == 2) { const int pn = n0 >> 8, j0 = n0 & 255; s0 = (j0 < 128) ? pn * 128 + j0 : DFF + pn * 128 + (j0 - 128); }
; #pragma unroll
;         for (int i = 0; i < 2; ++i) { const int idx = tid + 512 * i, kk = idx >> 4, n4 = idx & 15;
;             f32x4 v = {0.f, 0.f, 0.f, 0.f};
;             if (n4 * 4 < nvalid) v = *(const f32x4*)(src + (size_t)(k0 + kk) * Nsrc + s0 + n4 * 4);
;             const float gg = gain ? gain[k0 + kk] : 1.0f;
; #pragma unroll
;             for (int j = 0; j < 4; ++j) tile[kk * 65 + n4 * 4 + j] = v[j] * gg; }
;         __syncthreads();
;         { const int n = tid >> 3, k8 = tid & 7; float f[8];
; #pragma unroll
;             for (int j = 0; j < 8; ++j) f[j] = tile[(k8 * 8 + j) * 65 + n];
;             u32x4 w; w.x = pk_bf16(f[0], f[1]); w.y = pk_bf16(f[2], f[3]); w.z = pk_bf16(f[4], f[5]); w.w = pk_bf16(f[6], f[7]);
;             *(u32x4*)(dst + (size_t)(n0 + n) * ldd + koff + k0 + k8 * 8) = w; }
; __global__ void __launch_bounds__(512, 2) fwd_megakernel(Params p) {
;     ...
;         transpose_job(tile, p.w_in, WIN, p.norm1_g, 2048, 7696, NIN, 1);
;         transpose_job(tile, p.w_fin, WFIN, p.norm2_g, 2048, 2 * DFF, 2 * DFF, 2);
;         transpose_job(tile, p.w_fout, WFOUT, nullptr, DFF, 2048, 2048, 0);
;         transpose_job(tile, p.w_out, WOUT, nullptr, 2048, 2048, 2048, 0);
;         transpose_job(tile, p.w_ba, WA, nullptr, 1024, 2048, 2048, 0, KAB, 0);
;         transpose_job(tile, p.w_bb, WA, nullptr, 512, 2048, 2048, 0, KAB, 1024);
;         transpose_job(tile, p.w_glu, WGLU, nullptr, 512, 512, 512, 0);
.Lp0_nomul:
	v_cmp_gt_u32_e32 vcc, s21, v8
	v_cvt_pk_bf16_f32 v36, v28, v29
	v_cvt_pk_bf16_f32 v37, v30, v31
	v_cvt_pk_bf16_f32 v38, v32, v33
	v_cvt_pk_bf16_f32 v39, v34, v35
	s_nop 1
	v_cndmask_b32_e32 v36, 0, v36, vcc
	v_cndmask_b32_e32 v37, 0, v37, vcc
	v_cndmask_b32_e32 v38, 0, v38, vcc
	v_cndmask_b32_e32 v39, 0, v39, vcc
	global_store_dwordx4 v14, v[36:39], s[14:15]
	s_add_u32 s0, s0, s5
	s_add_u32 s1, s1, 1
	s_and_b32 s2, s1, 3
	s_lshl_b32 s2, s2, 14
	s_cmp_lt_u32 s0, s13
	s_cbranch_scc1 .Lp0_loop
	s_branch .Lp0_exit
.Lp0_dec:
	s_mov_b32 s21, 64
	s_mov_b32 s20, 0
	s_mov_b64 s[18:19], s[64:65]
	s_mov_b32 s45, 0x800
	s_cmp_lt_u32 s40, 0xf80
	s_cbranch_scc0 .Lp0_dec_n0
	s_lshr_b32 s41, s40, 5
	s_and_b32 s42, s40, 31
	s_lshl_b32 s43, s41, 6
	s_add_u32 s44, s43, 16
	s_cmp_lt_u32 s43, 0xc00
	s_cselect_b32 s44, s43, s44
	s_cmp_lt_u32 s43, 0x1e00
	s_cbranch_scc1 .Lp0_dec0_ok
	s_cmp_eq_u32 s43, 0x1e00
	s_cselect_b32 s44, 0xc00, 0
	s_cselect_b32 s21, 16, 0
.Lp0_dec0_ok:
	s_mov_b32 s45, 0x1e10
	s_mov_b32 s46, 0x800
	s_mov_b64 s[48:49], s[68:69]
	s_mov_b64 s[50:51], s[8:9]
	s_mov_b64 s[18:19], s[66:67]
	s_mov_b32 s20, 1
	s_branch .Lp0_dec_common

; #define LAS __attribute__((address_space(3)))
; #define SEAM(k) do { if (IN(k) && IN((k) + 1)) xcd_barrier(xbar); } while (0)
; __global__ void __launch_bounds__(512, 2) fwd_megakernel(Params p) {
;     ...
;     if (IN(0)) {
;         LAS float* tile = (LAS float*)lds;
;         transpose_job(tile, p.w_in, WIN, p.norm1_g, 2048, 7696, NIN, 1);
;         transpose_job(tile, p.w_fin, WFIN, p.norm2_g, 2048, 2 * DFF, 2 * DFF, 2);
;         transpose_job(tile, p.w_fout, WFOUT, nullptr, DFF, 2048, 2048, 0);
;         transpose_job(tile, p.w_out, WOUT, nullptr, 2048, 2048, 2048, 0);
;         transpose_job(tile, p.w_ba, WA, nullptr, 1024, 2048, 2048, 0, KAB, 0);
;         transpose_job(tile, p.w_bb, WA, nullptr, 512, 2048, 2048, 0, KAB, 1024);
;         transpose_job(tile, p.w_glu, WGLU, nullptr, 512, 512, 512, 0);
;         convert_x(p.x, XB, RSTD1);
;         for (int i = bid * 512 + threadIdx.x; i < MTOK; i += G * 512) { SSQ2[i] = 0ull; SSQ3[i] = 0ull; }
;     }
;     SEAM(0);
.Lp0_exit:
	s_cmp_eq_u32 s27, 0
	s_cbranch_scc0 .Lp1_ret

; #define SEAM(k) do { if (IN(k) && IN((k) + 1)) xcd_barrier(xbar); } while (0)
; __global__ void __launch_bounds__(512, 2) fwd_megakernel(Params p) {
;     ...
;         transpose_job(tile, p.w_in, WIN, p.norm1_g, 2048, 7696, NIN, 1);
;         transpose_job(tile, p.w_fin, WFIN, p.norm2_g, 2048, 2 * DFF, 2 * DFF, 2);
;         transpose_job(tile, p.w_fout, WFOUT, nullptr, DFF, 2048, 2048, 0);
;         transpose_job(tile, p.w_out, WOUT, nullptr, 2048, 2048, 2048, 0);
;         transpose_job(tile, p.w_ba, WA, nullptr, 1024, 2048, 2048, 0, KAB, 0);
;         transpose_job(tile, p.w_bb, WA, nullptr, 512, 2048, 2048, 0, KAB, 1024);
;         transpose_job(tile, p.w_glu, WGLU, nullptr, 512, 512, 512, 0);
;     ...
;     if (IN(1)) {
;         pg8::Gemm g{XB, WIN, MTOK, NIN, 2048}; pg8::StaticOrder S; S.init(MTOK, NIN, G, bid);
;         EpiIn E{(bf16_t*)(ws + WS_Q), (bf16_t*)(ws + WS_K), (bf16_t*)(ws + WS_V), (bf16_t*)(ws + WS_R), (bf16_t*)(ws + WS_U), (bf16_t*)(ws + WS_GA), (bf16_t*)(ws + WS_GB), (float*)(ws + WS_ALOW), RSTD1};
;         pg8::gemm_phase(lds, g, S, E);
;     }
;     ...
;     SEAM(1);
.LBB0_261:
	v_readlane_b32 s36, v246, 48
	v_readlane_b32 s37, v246, 49
	v_readlane_b32 s38, v246, 50
	v_readlane_b32 s39, v246, 51
	s_barrier
	v_writelane_b32 v247, s0, 0
	v_writelane_b32 v247, s1, 1
	v_writelane_b32 v247, s2, 2
	v_writelane_b32 v247, s3, 3
	v_writelane_b32 v247, s4, 4
	v_writelane_b32 v247, s5, 5
	v_writelane_b32 v247, s10, 6
	v_writelane_b32 v247, s11, 7
	v_writelane_b32 v247, s12, 8
	v_writelane_b32 v247, s13, 9
	v_writelane_b32 v247, s14, 10
	v_writelane_b32 v247, s15, 11
	v_writelane_b32 v247, s16, 12
	v_writelane_b32 v247, s17, 13
	v_writelane_b32 v247, s18, 14
	v_writelane_b32 v247, s19, 15
	v_writelane_b32 v247, s20, 16
	v_writelane_b32 v247, s21, 17
	v_writelane_b32 v247, s22, 18
	v_writelane_b32 v247, s23, 19
	v_writelane_b32 v247, s24, 20
	v_writelane_b32 v247, s25, 21
	v_writelane_b32 v247, s26, 22
	v_writelane_b32 v247, s27, 23
	v_writelane_b32 v247, s40, 24
	v_writelane_b32 v247, s41, 25
	v_writelane_b32 v247, s42, 26
	v_writelane_b32 v247, s43, 27
	v_writelane_b32 v247, s44, 28
	v_writelane_b32 v247, s45, 29
	v_writelane_b32 v247, s46, 30
	v_writelane_b32 v247, s47, 31
	v_writelane_b32 v247, s48, 32
	v_writelane_b32 v247, s49, 33
	v_writelane_b32 v247, s50, 34
	v_writelane_b32 v247, s51, 35
	v_writelane_b32 v247, s52, 36
	v_writelane_b32 v247, s53, 37
	v_writelane_b32 v247, s54, 38
	v_writelane_b32 v247, s55, 39
	s_cmp_eq_u32 s62, 0x100
	s_cbranch_scc0 .Lp1_all
	s_cmp_ge_u32 s96, 0x80
	s_cbranch_scc0 .Lp1_ret
	s_sub_u32 s17, s96, 0x80
	s_add_u32 s17, s17, 0xf80
	s_mov_b32 s5, 0x80
	s_branch .Lp1_go
.Lp1_all:
	s_add_u32 s17, s96, 0xf80
	s_mov_b32 s5, s62
.Lp1_go:
	s_mov_b32 s13, 0x37c0
	s_mov_b32 s27, 1
	s_branch .Lp0_entry
.Lp1_ret:
	v_readlane_b32 s0, v247, 0
	v_readlane_b32 s1, v247, 1
	v_readlane_b32 s2, v247, 2
	v_readlane_b32 s3, v247, 3
	v_readlane_b32 s4, v247, 4
	v_readlane_b32 s5, v247, 5
	v_readlane_b32 s10, v247, 6
	v_readlane_b32 s11, v247, 7
	v_readlane_b32 s12, v247, 8
	v_readlane_b32 s13, v247, 9
	v_readlane_b32 s14, v247, 10
	v_readlane_b32 s15, v247, 11
	v_readlane_b32 s16, v247, 12
	v_readlane_b32 s17, v247, 13
	v_readlane_b32 s18, v247, 14
	v_readlane_b32 s19, v247, 15
	v_readlane_b32 s20, v247, 16
	v_readlane_b32 s21, v247, 17
	v_readlane_b32 s22, v247, 18
	v_readlane_b32 s23, v247, 19
	v_readlane_b32 s24, v247, 20
	v_readlane_b32 s25, v247, 21
	v_readlane_b32 s26, v247, 22
	v_readlane_b32 s27, v247, 23
	v_readlane_b32 s40, v247, 24
	v_readlane_b32 s41, v247, 25
	v_readlane_b32 s42, v247, 26
	v_readlane_b32 s43, v247, 27
	v_readlane_b32 s44, v247, 28
	v_readlane_b32 s45, v247, 29
	v_readlane_b32 s46, v247, 30
	v_readlane_b32 s47, v247, 31
	v_readlane_b32 s48, v247, 32
	v_readlane_b32 s49, v247, 33
	v_readlane_b32 s50, v247, 34
	v_readlane_b32 s51, v247, 35
	v_readlane_b32 s52, v247, 36
	v_readlane_b32 s53, v247, 37
	v_readlane_b32 s54, v247, 38
	v_readlane_b32 s55, v247, 39
	s_nop 3

; __global__ void __launch_bounds__(512, 2) fwd_megakernel(Params p) {
;     extern __shared__ __attribute__((aligned(16))) unsigned char smem[];
;     cg::grid_group grid = cg::this_grid();
;     const ldsp lds = (ldsp)smem;
	.amdhsa_kernel _Z14fwd_megakernel6Params
		.amdhsa_group_segment_fixed_size 0
		.amdhsa_private_segment_fixed_size 0
		.amdhsa_kernarg_size 464
		.amdhsa_user_sgpr_count 2
		.amdhsa_user_sgpr_dispatch_ptr 0
		.amdhsa_user_sgpr_queue_ptr 0
		.amdhsa_user_sgpr_kernarg_segment_ptr 1
		.amdhsa_user_sgpr_dispatch_id 0
		.amdhsa_user_sgpr_kernarg_preload_length 0
		.amdhsa_user_sgpr_kernarg_preload_offset 0
		.amdhsa_user_sgpr_private_segment_size 0
		.amdhsa_uses_dynamic_stack 0
		.amdhsa_enable_private_segment 0
		.amdhsa_system_sgpr_workgroup_id_x 1
		.amdhsa_system_sgpr_workgroup_id_y 0
		.amdhsa_system_sgpr_workgroup_id_z 0
		.amdhsa_system_sgpr_workgroup_info 0
		.amdhsa_system_vgpr_workitem_id 2
		.amdhsa_next_free_vgpr 248
		.amdhsa_next_free_sgpr 98
		.amdhsa_accum_offset 248
		.amdhsa_reserve_vcc 1
		.amdhsa_float_round_mode_32 0
		.amdhsa_float_round_mode_16_64 0
		.amdhsa_float_denorm_mode_32 3
		.amdhsa_float_denorm_mode_16_64 3
		.amdhsa_dx10_clamp 1
		.amdhsa_ieee_mode 1
		.amdhsa_fp16_overflow 0
		.amdhsa_tg_split 0
		.amdhsa_exception_fp_ieee_invalid_op 0
		.amdhsa_exception_fp_denorm_src 0
		.amdhsa_exception_fp_ieee_div_zero 0
		.amdhsa_exception_fp_ieee_overflow 0
		.amdhsa_exception_fp_ieee_underflow 0
		.amdhsa_exception_fp_ieee_inexact 0
		.amdhsa_exception_int_div_zero 0
	.end_amdhsa_kernel

; __global__ void __launch_bounds__(512, 2) fwd_megakernel(Params p) {
;     extern __shared__ __attribute__((aligned(16))) unsigned char smem[];
;     cg::grid_group grid = cg::this_grid();
;     const ldsp lds = (ldsp)smem;
amdhsa.kernels:
  - .agpr_count:     0
    .args:
      - .offset:         0
        .size:           208
        .value_kind:     by_value
      - .offset:         208
        .size:           4
        .value_kind:     hidden_block_count_x
      - .offset:         212
        .size:           4
        .value_kind:     hidden_block_count_y
      - .offset:         216
        .size:           4
        .value_kind:     hidden_block_count_z
      - .offset:         220
        .size:           2
        .value_kind:     hidden_group_size_x
      - .offset:         222
        .size:           2
        .value_kind:     hidden_group_size_y
      - .offset:         224
        .size:           2
        .value_kind:     hidden_group_size_z
      - .offset:         226
        .size:           2
        .value_kind:     hidden_remainder_x
      - .offset:         228
        .size:           2
        .value_kind:     hidden_remainder_y
      - .offset:         230
        .size:           2
        .value_kind:     hidden_remainder_z
      - .offset:         248
        .size:           8
        .value_kind:     hidden_global_offset_x
      - .offset:         256
        .size:           8
        .value_kind:     hidden_global_offset_y
      - .offset:         264
        .size:           8
        .value_kind:     hidden_global_offset_z
      - .offset:         272
        .size:           2
        .value_kind:     hidden_grid_dims
      - .offset:         296
        .size:           8
        .value_kind:     hidden_multigrid_sync_arg
      - .offset:         328
        .size:           4
        .value_kind:     hidden_dynamic_lds_size
    .group_segment_fixed_size: 0
    .kernarg_segment_align: 8
    .kernarg_segment_size: 464
    .language:       OpenCL C
    .language_version:
      - 2
      - 0
    .max_flat_workgroup_size: 512
    .name:           _Z14fwd_megakernel6Params
    .private_segment_fixed_size: 0
    .sgpr_count:     104
    .sgpr_spill_count: 63
    .symbol:         _Z14fwd_megakernel6Params.kd
    .uniform_work_group_size: 1
    .uses_dynamic_stack: false
    .vgpr_count:     248
    .vgpr_spill_count: 0
    .wavefront_size: 64
